# P7 K/V units of prompt panels: straight-line epilogue (f32 rows + permlane-paired 16-byte bf16 copies), no per-lane branches
# speedup vs baseline: 1.2237x; 1.0099x over previous
.Lp7_epi_kv:
	s_cmp_gt_u32 s10, 63
	s_cbranch_scc1 .Lp7_epi_orig
	v_lshl_add_u32 v2, s10, 8, v240
	v_lshl_or_b32 v132, s58, 8, v242
	s_mov_b32 s16, 0x8100000
	s_cmp_gt_u32 s58, 5
	s_cselect_b32 s16, 0xe100000, s16
	s_cselect_b32 s17, 0x1800, 0
	s_cselect_b32 s14, s71, s3
	s_cselect_b32 s15, s72, s33
	s_add_u32 s12, s48, s16
	s_addc_u32 s13, s49, 0
	s_lshr_b32 s18, s17, 1
	v_bfe_u32 v138, v242, 2, 1
	v_mul_u32_u24_e32 v138, 24, v138
	v_lshl_add_u32 v138, v132, 1, v138
	v_subrev_u32_e32 v138, s18, v138
	v_lshlrev_b32_e32 v136, 2, v132
	v_subrev_u32_e32 v136, s17, v136
	v_mul_u32_u24_e32 v3, 0x1800, v2
	v_add_u32_e32 v140, v3, v136
	v_lshrrev_b32_e32 v3, 1, v3
	v_add_u32_e32 v148, v3, v138
	v_add_u32_e32 v141, 0x18000, v140
	v_add_u32_e32 v149, 0xc000, v148
	v_add_u32_e32 v142, 0x30000, v140
	v_add_u32_e32 v150, 0x18000, v148
	v_add_u32_e32 v143, 0x48000, v140
	v_add_u32_e32 v151, 0x24000, v148
	v_add_u32_e32 v144, 0xc0000, v140
	v_add_u32_e32 v152, 0x60000, v148
	v_add_u32_e32 v145, 0xd8000, v140
	v_add_u32_e32 v153, 0x6c000, v148
	v_add_u32_e32 v146, 0xf0000, v140
	v_add_u32_e32 v154, 0x78000, v148
	v_add_u32_e32 v147, 0x108000, v140
	v_add_u32_e32 v155, 0x84000, v148
	s_nop 7
	global_store_dwordx4 v140, v[128:131], s[12:13]
	global_store_dwordx4 v140, v[124:127], s[12:13] offset:64
	global_store_dwordx4 v140, v[120:123], s[12:13] offset:512
	global_store_dwordx4 v140, v[116:119], s[12:13] offset:576
	s_nop 1
	v_cvt_pk_bf16_f32 v128, v128, v129
	v_cvt_pk_bf16_f32 v129, v130, v131
	v_cvt_pk_bf16_f32 v130, v124, v125
	v_cvt_pk_bf16_f32 v131, v126, v127
	v_cvt_pk_bf16_f32 v120, v120, v121
	v_cvt_pk_bf16_f32 v121, v122, v123
	v_cvt_pk_bf16_f32 v122, v116, v117
	v_cvt_pk_bf16_f32 v123, v118, v119
	s_nop 1
	v_permlane16_swap_b32_e32 v128, v130
	v_permlane16_swap_b32_e32 v129, v131
	v_permlane16_swap_b32_e32 v120, v122
	v_permlane16_swap_b32_e32 v121, v123
	global_store_dwordx4 v148, v[128:131], s[14:15]
	global_store_dwordx4 v148, v[120:123], s[14:15] offset:256
	global_store_dwordx4 v141, v[112:115], s[12:13]
	global_store_dwordx4 v141, v[108:111], s[12:13] offset:64
	global_store_dwordx4 v141, v[104:107], s[12:13] offset:512
	global_store_dwordx4 v141, v[100:103], s[12:13] offset:576
	s_nop 1
	v_cvt_pk_bf16_f32 v112, v112, v113
	v_cvt_pk_bf16_f32 v113, v114, v115
	v_cvt_pk_bf16_f32 v114, v108, v109
	v_cvt_pk_bf16_f32 v115, v110, v111
	v_cvt_pk_bf16_f32 v104, v104, v105
	v_cvt_pk_bf16_f32 v105, v106, v107
	v_cvt_pk_bf16_f32 v106, v100, v101
	v_cvt_pk_bf16_f32 v107, v102, v103
	s_nop 1
	v_permlane16_swap_b32_e32 v112, v114
	v_permlane16_swap_b32_e32 v113, v115
	v_permlane16_swap_b32_e32 v104, v106
	v_permlane16_swap_b32_e32 v105, v107
	global_store_dwordx4 v149, v[112:115], s[14:15]
	global_store_dwordx4 v149, v[104:107], s[14:15] offset:256
	global_store_dwordx4 v142, v[96:99], s[12:13]
	global_store_dwordx4 v142, v[92:95], s[12:13] offset:64
	global_store_dwordx4 v142, v[88:91], s[12:13] offset:512
	global_store_dwordx4 v142, v[84:87], s[12:13] offset:576
	s_nop 1
	v_cvt_pk_bf16_f32 v96, v96, v97
	v_cvt_pk_bf16_f32 v97, v98, v99
	v_cvt_pk_bf16_f32 v98, v92, v93
	v_cvt_pk_bf16_f32 v99, v94, v95
	v_cvt_pk_bf16_f32 v88, v88, v89
	v_cvt_pk_bf16_f32 v89, v90, v91
	v_cvt_pk_bf16_f32 v90, v84, v85
	v_cvt_pk_bf16_f32 v91, v86, v87
	s_nop 1
	v_permlane16_swap_b32_e32 v96, v98
	v_permlane16_swap_b32_e32 v97, v99
	v_permlane16_swap_b32_e32 v88, v90
	v_permlane16_swap_b32_e32 v89, v91
	global_store_dwordx4 v150, v[96:99], s[14:15]
	global_store_dwordx4 v150, v[88:91], s[14:15] offset:256
	global_store_dwordx4 v143, v[80:83], s[12:13]
	global_store_dwordx4 v143, v[76:79], s[12:13] offset:64
	global_store_dwordx4 v143, v[72:75], s[12:13] offset:512
	global_store_dwordx4 v143, v[68:71], s[12:13] offset:576
	s_nop 1
	v_cvt_pk_bf16_f32 v80, v80, v81
	v_cvt_pk_bf16_f32 v81, v82, v83
	v_cvt_pk_bf16_f32 v82, v76, v77
	v_cvt_pk_bf16_f32 v83, v78, v79
	v_cvt_pk_bf16_f32 v72, v72, v73
	v_cvt_pk_bf16_f32 v73, v74, v75
	v_cvt_pk_bf16_f32 v74, v68, v69
	v_cvt_pk_bf16_f32 v75, v70, v71
	s_nop 1
	v_permlane16_swap_b32_e32 v80, v82
	v_permlane16_swap_b32_e32 v81, v83
	v_permlane16_swap_b32_e32 v72, v74
	v_permlane16_swap_b32_e32 v73, v75
	global_store_dwordx4 v151, v[80:83], s[14:15]
	global_store_dwordx4 v151, v[72:75], s[14:15] offset:256
	global_store_dwordx4 v144, v[64:67], s[12:13]
	global_store_dwordx4 v144, v[60:63], s[12:13] offset:64
	global_store_dwordx4 v144, v[56:59], s[12:13] offset:512
	global_store_dwordx4 v144, v[52:55], s[12:13] offset:576
	s_nop 1
	v_cvt_pk_bf16_f32 v64, v64, v65
	v_cvt_pk_bf16_f32 v65, v66, v67
	v_cvt_pk_bf16_f32 v66, v60, v61
	v_cvt_pk_bf16_f32 v67, v62, v63
	v_cvt_pk_bf16_f32 v56, v56, v57
	v_cvt_pk_bf16_f32 v57, v58, v59
	v_cvt_pk_bf16_f32 v58, v52, v53
	v_cvt_pk_bf16_f32 v59, v54, v55
	s_nop 1
	v_permlane16_swap_b32_e32 v64, v66
	v_permlane16_swap_b32_e32 v65, v67
	v_permlane16_swap_b32_e32 v56, v58
	v_permlane16_swap_b32_e32 v57, v59
	global_store_dwordx4 v152, v[64:67], s[14:15]
	global_store_dwordx4 v152, v[56:59], s[14:15] offset:256
	global_store_dwordx4 v145, v[48:51], s[12:13]
	global_store_dwordx4 v145, v[44:47], s[12:13] offset:64
	global_store_dwordx4 v145, v[40:43], s[12:13] offset:512
	global_store_dwordx4 v145, v[36:39], s[12:13] offset:576
	s_nop 1
	v_cvt_pk_bf16_f32 v48, v48, v49
	v_cvt_pk_bf16_f32 v49, v50, v51
	v_cvt_pk_bf16_f32 v50, v44, v45
	v_cvt_pk_bf16_f32 v51, v46, v47
	v_cvt_pk_bf16_f32 v40, v40, v41
	v_cvt_pk_bf16_f32 v41, v42, v43
	v_cvt_pk_bf16_f32 v42, v36, v37
	v_cvt_pk_bf16_f32 v43, v38, v39
	s_nop 1
	v_permlane16_swap_b32_e32 v48, v50
	v_permlane16_swap_b32_e32 v49, v51
	v_permlane16_swap_b32_e32 v40, v42
	v_permlane16_swap_b32_e32 v41, v43
	global_store_dwordx4 v153, v[48:51], s[14:15]
	global_store_dwordx4 v153, v[40:43], s[14:15] offset:256
	global_store_dwordx4 v146, v[32:35], s[12:13]
	global_store_dwordx4 v146, v[28:31], s[12:13] offset:64
	global_store_dwordx4 v146, v[24:27], s[12:13] offset:512
	global_store_dwordx4 v146, v[20:23], s[12:13] offset:576
	s_nop 1
	v_cvt_pk_bf16_f32 v32, v32, v33
	v_cvt_pk_bf16_f32 v33, v34, v35
	v_cvt_pk_bf16_f32 v34, v28, v29
	v_cvt_pk_bf16_f32 v35, v30, v31
	v_cvt_pk_bf16_f32 v24, v24, v25
	v_cvt_pk_bf16_f32 v25, v26, v27
	v_cvt_pk_bf16_f32 v26, v20, v21
	v_cvt_pk_bf16_f32 v27, v22, v23
	s_nop 1
	v_permlane16_swap_b32_e32 v32, v34
	v_permlane16_swap_b32_e32 v33, v35
	v_permlane16_swap_b32_e32 v24, v26
	v_permlane16_swap_b32_e32 v25, v27
	global_store_dwordx4 v154, v[32:35], s[14:15]
	global_store_dwordx4 v154, v[24:27], s[14:15] offset:256
	global_store_dwordx4 v147, v[16:19], s[12:13]
	global_store_dwordx4 v147, v[12:15], s[12:13] offset:64
	global_store_dwordx4 v147, v[8:11], s[12:13] offset:512
	global_store_dwordx4 v147, v[4:7], s[12:13] offset:576
	s_nop 1
	v_cvt_pk_bf16_f32 v16, v16, v17
	v_cvt_pk_bf16_f32 v17, v18, v19
	v_cvt_pk_bf16_f32 v18, v12, v13
	v_cvt_pk_bf16_f32 v19, v14, v15
	v_cvt_pk_bf16_f32 v8, v8, v9
	v_cvt_pk_bf16_f32 v9, v10, v11
	v_cvt_pk_bf16_f32 v10, v4, v5
	v_cvt_pk_bf16_f32 v11, v6, v7
	s_nop 1
	v_permlane16_swap_b32_e32 v16, v18
	v_permlane16_swap_b32_e32 v17, v19
	v_permlane16_swap_b32_e32 v8, v10
	v_permlane16_swap_b32_e32 v9, v11
	global_store_dwordx4 v155, v[16:19], s[14:15]
	global_store_dwordx4 v155, v[8:11], s[14:15] offset:256
	s_mov_b64 s[8:9], exec
	s_branch .LBB0_534
